# speedup vs baseline: 1.0294x; 1.0012x over previous
; __device__ __forceinline__ unsigned cvt_pk_bf16(float lo, float hi) { unsigned r; asm volatile("v_cvt_pk_bf16_f32 %0, %1, %2" : "=v"(r) : "v"(lo), "v"(hi)); return r; }
; __device__ __forceinline__ void prep_phase(const Params& p, LAS unsigned char* lds) {
;     ...
;     {
;         bf16_t* xb = (bf16_t*)(p.ws + WS_XB);
;         for (int xi = blockIdx.x; xi < PREP_X; xi += gridDim.x) {
; #pragma unroll
;             for (int it = 0; it < 4; ++it) { const size_t e = ((size_t)xi * 2048 + tid + it * 512) * 4;
;                 const float* sp = e < (size_t)MP * DM ? p.x_prompt + e : p.x_sample + (e - (size_t)MP * DM);
;                 const f32x4 v = *(const f32x4*)sp;
;                 u32x2 w; w.x = cvt_pk_bf16(v[0], v[1]); w.y = cvt_pk_bf16(v[2], v[3]); *(u32x2*)(xb + (e >> 11) * LDX + (e & 2047)) = w; }
;         }
.LBB0_1577:
	s_ashr_i32 s1, s0, 31
	s_lshl_b64 s[2:3], s[0:1], 13
	v_lshl_add_u64 v[10:11], s[2:3], 0, v[0:1]
	s_mov_b64 s[2:3], 0x800
	v_lshl_add_u64 v[12:13], v[10:11], 0, s[2:3]
	s_mov_b64 s[2:3], 0x1000
	v_lshl_add_u64 v[14:15], v[10:11], 0, s[2:3]
	s_mov_b64 s[2:3], 0x1800
	v_lshl_add_u64 v[48:49], v[10:11], 0, s[2:3]
	s_brev_b32 s2, 63
	s_mov_b32 s3, -1
	v_lshlrev_b64 v[50:51], 2, v[10:11]
	v_cmp_gt_u64_e32 vcc, s[4:5], v[10:11]
	v_lshl_add_u64 v[52:53], s[48:49], 0, v[50:51]
	v_lshl_add_u64 v[50:51], s[50:51], 0, v[50:51]
	v_lshl_add_u64 v[50:51], v[50:51], 0, s[2:3]
	v_cndmask_b32_e32 v51, v51, v53, vcc
	v_cndmask_b32_e32 v50, v50, v52, vcc
	global_load_dwordx4 v[32:35], v[50:51], off
	v_lshlrev_b64 v[50:51], 2, v[12:13]
	v_cmp_gt_u64_e32 vcc, s[4:5], v[12:13]
	v_lshl_add_u64 v[52:53], s[48:49], 0, v[50:51]
	v_lshl_add_u64 v[50:51], s[50:51], 0, v[50:51]
	v_lshl_add_u64 v[50:51], v[50:51], 0, s[2:3]
	v_cndmask_b32_e32 v51, v51, v53, vcc
	v_cndmask_b32_e32 v50, v50, v52, vcc
	global_load_dwordx4 v[36:39], v[50:51], off
	v_lshlrev_b64 v[50:51], 2, v[14:15]
	v_cmp_gt_u64_e32 vcc, s[4:5], v[14:15]
	v_lshl_add_u64 v[52:53], s[48:49], 0, v[50:51]
	v_lshl_add_u64 v[50:51], s[50:51], 0, v[50:51]
	v_lshl_add_u64 v[50:51], v[50:51], 0, s[2:3]
	v_cndmask_b32_e32 v51, v51, v53, vcc
	v_cndmask_b32_e32 v50, v50, v52, vcc
	global_load_dwordx4 v[40:43], v[50:51], off
	v_lshlrev_b64 v[50:51], 2, v[48:49]
	v_cmp_gt_u64_e32 vcc, s[4:5], v[48:49]
	v_lshl_add_u64 v[52:53], s[48:49], 0, v[50:51]
	v_lshl_add_u64 v[50:51], s[50:51], 0, v[50:51]
	v_lshl_add_u64 v[50:51], v[50:51], 0, s[2:3]
	v_cndmask_b32_e32 v51, v51, v53, vcc
	v_cndmask_b32_e32 v50, v50, v52, vcc
	global_load_dwordx4 v[44:47], v[50:51], off
	s_waitcnt vmcnt(3)
	v_cvt_pk_bf16_f32 v32, v32, v33
	v_cvt_pk_bf16_f32 v33, v34, v35
	v_alignbit_b32 v50, v11, v10, 11
	v_lshrrev_b32_e32 v52, 11, v11
	v_mad_u64_u32 v[50:51], s[2:3], v50, s93, v[2:3]
	v_mad_u32_u24 v51, v52, s93, v51
	global_store_dwordx2 v[50:51], v[32:33], off
	s_waitcnt vmcnt(3)
	v_cvt_pk_bf16_f32 v36, v36, v37
	v_cvt_pk_bf16_f32 v37, v38, v39
	v_alignbit_b32 v50, v13, v12, 11
	v_lshrrev_b32_e32 v52, 11, v13
	v_mad_u64_u32 v[50:51], s[2:3], v50, s93, v[2:3]
	v_mad_u32_u24 v51, v52, s93, v51
	global_store_dwordx2 v[50:51], v[36:37], off
	s_waitcnt vmcnt(3)
	v_cvt_pk_bf16_f32 v40, v40, v41
	v_cvt_pk_bf16_f32 v41, v42, v43
	v_alignbit_b32 v50, v15, v14, 11
	v_lshrrev_b32_e32 v52, 11, v15
	v_mad_u64_u32 v[50:51], s[2:3], v50, s93, v[2:3]
	v_mad_u32_u24 v51, v52, s93, v51
	global_store_dwordx2 v[50:51], v[40:41], off
	s_waitcnt vmcnt(3)
	v_cvt_pk_bf16_f32 v44, v44, v45
	v_cvt_pk_bf16_f32 v45, v46, v47
	v_alignbit_b32 v50, v49, v48, 11
	v_lshrrev_b32_e32 v52, 11, v49
	v_mad_u64_u32 v[50:51], s[2:3], v50, s93, v[2:3]
	v_mad_u32_u24 v51, v52, s93, v51
	global_store_dwordx2 v[50:51], v[44:45], off
	s_load_dword s1, s[90:91], 0x10
	s_waitcnt lgkmcnt(0)
	s_lshr_b32 s1, s1, 16
	s_cmp_lg_u32 s1, 0
	s_cselect_b64 s[2:3], -1, 0
	s_cmp_lg_u64 s[2:3], 0
	s_addc_u32 s0, s0, s86
	s_cmpk_gt_i32 s0, 0x8ff
	s_cbranch_scc0 .LBB0_1577
	v_readlane_b32 s2, v252, 48
	v_readlane_b32 s3, v252, 49
	s_branch .LBB0_1580
